# static s_setprio 1 raise applied to waves 0-3 (the other physical half) instead of waves 4-7, to confirm which half nets more under a role-alternating K-loop
# speedup vs baseline: 1.0150x; 1.0004x over previous
; __device__ __forceinline__ int tid_now(int wave_s) { int l; asm volatile("v_mbcnt_lo_u32_b32 %0, -1, 0\n\tv_mbcnt_hi_u32_b32 %0, -1, %0" : "=v"(l)); return (wave_s << 6) | l; }
; #define LAS __attribute__((address_space(3)))
; __device__ __forceinline__ unsigned xb_ld(unsigned* p)              { return __hip_atomic_load(p, __ATOMIC_RELAXED, __HIP_MEMORY_SCOPE_AGENT); }
; __device__ __forceinline__ unsigned xb_add(unsigned* p, unsigned v) { return __hip_atomic_fetch_add(p, v, __ATOMIC_RELAXED, __HIP_MEMORY_SCOPE_AGENT); }
; __device__ __forceinline__ unsigned xb_xcc_id() { return (unsigned)__builtin_amdgcn_s_getreg((3 << 11) | 20) & 0xFu; }
; template <class Epi, class Sched, bool ALIGN_EPI = false, bool SP2 = false>
; __device__ __forceinline__ void gemm_phase(PG8_LAS unsigned char* lds, const Gemm g, const Sched& S, const Epi& E, int wave_s) {
;     const int tid_ = tid_now(wave_s);
;     const int tid = tid_, wid = __builtin_amdgcn_readfirstlane(tid >> 6), lane = tid & 63, wr = wid >> 2, wc = wid & 3, fr = lane & 15, fq = lane >> 4;
; __global__ void __launch_bounds__(NTHR, 2) fwd_kernel(Args a_in) {
;     extern __shared__ __attribute__((aligned(16))) unsigned char lds_raw[];
;     LAS unsigned char* lds = (LAS unsigned char*)lds_raw;
;     cg::grid_group grid = cg::this_grid();
;     if (threadIdx.x == 0) { volatile LAS unsigned* st = (volatile LAS unsigned*)(lds + XB_LDS_OFF); st[0] = 0u; st[1] = 0u; const unsigned x_ = xb_xcc_id(); st[2] = x_; st[3] = xb_add((unsigned*)(a_in.ws + WS_BAR) + XB_XCNT(x_), 1u); }
;     for (int rp_ = 0; rp_ < REP_PRO; ++rp_) prologue_phase(a_in, lds);
;     const int wave_s = __builtin_amdgcn_readfirstlane(threadIdx.x >> 6);
;     if (gridDim.x == 0x7fffffffu) grid.sync();
;     grid_bar(wave_s);
;     if (threadIdx.x == 0) { volatile LAS unsigned* st = (volatile LAS unsigned*)(lds + XB_LDS_OFF); unsigned* bw = (unsigned*)(a_in.ws + WS_BAR); bool ok = gridDim.x == 256;
;         for (int j = 0; j < 16; ++j) { const unsigned c_ = xb_ld(bw + XB_XCNT(j)); ok = ok && (c_ == (j < 8 ? 32u : 0u)); }
;         st[4] = ok ? (st[2] + 8u * st[3]) : (unsigned)blockIdx.x; }
;     __syncthreads();
;     const int cu_idx = __builtin_amdgcn_readfirstlane((int)((volatile LAS unsigned*)(lds + XB_LDS_OFF))[4]);
.LBB0_4:
	s_or_b64 exec, exec, s[2:3]
	v_writelane_b32 v255, s0, 1
	s_load_dwordx4 s[20:23], s[0:1], 0x40
	v_mov_b32_e32 v2, v1
	v_writelane_b32 v255, s1, 2
	s_waitcnt lgkmcnt(0)
	s_lshl_b32 s24, s38, 3
	v_readlane_b32 s0, v255, 0
	v_readfirstlane_b32 s3, v2
	s_lshl_b32 s0, s0, 3
	s_ashr_i32 s2, s3, 6
	s_cmp_ge_i32 s2, 4
	s_cbranch_scc1 .Lprio_done
	s_setprio 1
